# norm phases: wave_sum via DPP row ops + row_bcast + readlane instead of 6 ds_bpermute round trips
# speedup vs baseline: 1.0101x; 1.0033x over previous
.LBB0_206:
	s_or_b64 exec, exec, s[20:21]
	v_cndmask_b32_e32 v2, 0, v20, vcc
	v_lshl_add_u64 v[22:23], s[10:11], 0, v[2:3]
	v_lshl_add_u64 v[70:71], v[22:23], 0, v[8:9]
	v_lshl_add_u64 v[12:13], v[12:13], 0, v[8:9]
	v_add_co_u32_e32 v74, vcc, 0x1000, v70
	v_lshl_add_u64 v[72:73], v[70:71], 0, s[18:19]
	s_nop 0
	v_addc_co_u32_e32 v75, vcc, 0, v71, vcc
	global_load_dwordx4 v[22:25], v[12:13], off
	global_load_dwordx4 v[26:29], v[12:13], off offset:1024
	global_load_dwordx4 v[30:33], v[70:71], off
	global_load_dwordx4 v[34:37], v[70:71], off offset:1024
	global_load_dwordx4 v[38:41], v[72:73], off offset:1024
	global_load_dwordx4 v[42:45], v[72:73], off offset:2048
	global_load_dwordx4 v[46:49], v[12:13], off offset:2048
	global_load_dwordx4 v[50:53], v[12:13], off offset:3072
	global_load_dwordx4 v[54:57], v[70:71], off offset:2048
	global_load_dwordx4 v[58:61], v[70:71], off offset:3072
	global_load_dwordx4 v[62:65], v[74:75], off
	global_load_dwordx4 v[66:69], v[72:73], off offset:3072
	s_waitcnt vmcnt(11)
	v_pk_mul_f32 v[12:13], v[24:25], v[24:25]
	v_pk_mul_f32 v[70:71], v[22:23], v[22:23]
	s_waitcnt vmcnt(4)
	v_mul_f32_e32 v2, v50, v50
	v_pk_mov_b32 v[72:73], v[70:71], v[12:13] op_sel:[1,0]
	v_mov_b32_e32 v71, v13
	v_pk_add_f32 v[12:13], v[72:73], v[70:71]
	v_pk_mul_f32 v[70:71], v[28:29], v[28:29]
	v_pk_mul_f32 v[72:73], v[26:27], v[26:27]
	v_pk_add_f32 v[12:13], v[12:13], v[12:13] op_sel:[0,1] op_sel_hi:[1,0]
	v_pk_mov_b32 v[74:75], v[72:73], v[70:71] op_sel:[1,0]
	v_mov_b32_e32 v73, v71
	v_pk_add_f32 v[70:71], v[74:75], v[72:73]
	v_mul_f32_e32 v72, v51, v51
	v_pk_add_f32 v[70:71], v[70:71], v[70:71] op_sel:[0,1] op_sel_hi:[1,0]
	v_mov_b32_e32 v13, v2
	v_mov_b32_e32 v71, v72
	v_mul_f32_e32 v2, v47, v47
	v_mul_f32_e32 v73, v52, v52
	v_pk_add_f32 v[12:13], v[12:13], v[70:71]
	v_pk_fma_f32 v[70:71], v[46:47], v[46:47], v[2:3] op_sel_hi:[1,1,0]
	v_mul_f32_e32 v2, v49, v49
	v_mul_f32_e32 v74, v53, v53
	v_mov_b32_e32 v71, v73
	v_pk_fma_f32 v[72:73], v[48:49], v[48:49], v[2:3] op_sel_hi:[1,1,0]
	s_waitcnt vmcnt(1)
	v_pk_add_f32 v[62:63], v[62:63], 1.0 op_sel_hi:[1,0]
	v_mov_b32_e32 v73, v74
	v_pk_add_f32 v[70:71], v[70:71], v[72:73]
	v_lshlrev_b64 v[10:11], 11, v[10:11]
	v_pk_add_f32 v[12:13], v[12:13], v[70:71]
	v_lshl_add_u64 v[10:11], v[4:5], 0, v[10:11]
	v_add_f32_e32 v2, v12, v13
	s_nop 1
	v_add_f32_dpp v2, v2, v2 quad_perm:[1,0,3,2] row_mask:0xf bank_mask:0xf
	v_lshl_add_u64 v[0:1], v[0:1], 0, s[12:13]
	v_lshl_add_u64 v[6:7], v[6:7], 0, s[14:15]
	s_nop 1
	v_add_f32_dpp v2, v2, v2 quad_perm:[2,3,0,1] row_mask:0xf bank_mask:0xf
	s_nop 1
	v_add_f32_dpp v2, v2, v2 row_half_mirror row_mask:0xf bank_mask:0xf
	s_nop 1
	v_add_f32_dpp v2, v2, v2 row_mirror row_mask:0xf bank_mask:0xf
	s_nop 1
	v_add_f32_dpp v2, v2, v2 row_bcast:15 row_mask:0xa bank_mask:0xf
	s_nop 1
	v_add_f32_dpp v2, v2, v2 row_bcast:31 row_mask:0xc bank_mask:0xf
	s_nop 1
	v_readlane_b32 s98, v2, 63
	s_nop 3
	v_mov_b32_e32 v2, s98
	v_fmamk_f32 v2, v2, 0x3a800000, v21
	v_mul_f32_e32 v12, 0x4b800000, v2
	v_cmp_gt_f32_e32 vcc, s23, v2
	s_nop 1
	v_cndmask_b32_e32 v2, v2, v12, vcc
	v_rsq_f32_e32 v2, v2
	v_pk_add_f32 v[12:13], v[64:65], 1.0 op_sel_hi:[1,0]
	v_mul_f32_e32 v64, 0x45800000, v2
	v_cndmask_b32_e32 v2, v2, v64, vcc
	v_pk_mul_f32 v[22:23], v[22:23], v[2:3] op_sel_hi:[1,0]
	v_pk_mul_f32 v[24:25], v[24:25], v[2:3] op_sel_hi:[1,0]
	v_pk_fma_f32 v[22:23], v[62:63], v[22:23], v[30:31]
	v_pk_fma_f32 v[12:13], v[12:13], v[24:25], v[32:33]
	v_cvt_pk_bf16_f32 v22, v22, v23
	v_cvt_pk_bf16_f32 v23, v12, v13
	global_store_dwordx2 v[10:11], v[22:23], off
	v_pk_mul_f32 v[12:13], v[26:27], v[2:3] op_sel_hi:[1,0]
	v_pk_mul_f32 v[22:23], v[28:29], v[2:3] op_sel_hi:[1,0]
	v_pk_add_f32 v[24:25], v[40:41], 1.0 op_sel_hi:[1,0]
	v_pk_add_f32 v[26:27], v[38:39], 1.0 op_sel_hi:[1,0]
	v_pk_fma_f32 v[22:23], v[24:25], v[22:23], v[36:37]
	v_pk_fma_f32 v[12:13], v[26:27], v[12:13], v[34:35]
	v_pk_add_f32 v[24:25], v[44:45], 1.0 op_sel_hi:[1,0]
	v_cvt_pk_bf16_f32 v12, v12, v13
	v_cvt_pk_bf16_f32 v13, v22, v23
	global_store_dwordx2 v[10:11], v[12:13], off offset:512
	v_pk_mul_f32 v[12:13], v[46:47], v[2:3] op_sel_hi:[1,0]
	v_pk_mul_f32 v[22:23], v[48:49], v[2:3] op_sel_hi:[1,0]
	v_pk_add_f32 v[26:27], v[42:43], 1.0 op_sel_hi:[1,0]
	v_pk_fma_f32 v[22:23], v[24:25], v[22:23], v[56:57]
	v_pk_fma_f32 v[12:13], v[26:27], v[12:13], v[54:55]
	s_waitcnt vmcnt(2)
	v_pk_add_f32 v[24:25], v[68:69], 1.0 op_sel_hi:[1,0]
	v_cvt_pk_bf16_f32 v12, v12, v13
	v_cvt_pk_bf16_f32 v13, v22, v23
	global_store_dwordx2 v[10:11], v[12:13], off offset:1024
	v_pk_mul_f32 v[12:13], v[50:51], v[2:3] op_sel_hi:[1,0]
	v_pk_mul_f32 v[22:23], v[52:53], v[2:3] op_sel_hi:[1,0]
	v_pk_add_f32 v[26:27], v[66:67], 1.0 op_sel_hi:[1,0]
	v_pk_fma_f32 v[22:23], v[24:25], v[22:23], v[60:61]
	v_pk_fma_f32 v[12:13], v[26:27], v[12:13], v[58:59]
	v_cmp_lt_i32_e32 vcc, s24, v0
	v_cvt_pk_bf16_f32 v12, v12, v13
	v_cvt_pk_bf16_f32 v13, v22, v23
	s_or_b64 s[16:17], vcc, s[16:17]
	global_store_dwordx2 v[10:11], v[12:13], off offset:1536
	s_andn2_b64 exec, exec, s[16:17]
	s_cbranch_execz .LBB0_209

.LBB0_419:
	s_or_b64 exec, exec, s[22:23]
	v_cndmask_b32_e32 v2, 0, v20, vcc
	v_lshl_add_u64 v[22:23], s[10:11], 0, v[2:3]
	v_lshl_add_u64 v[22:23], v[22:23], 0, v[8:9]
	v_add_co_u32_e32 v74, vcc, 0x3000, v22
	v_lshl_add_u64 v[12:13], v[12:13], 0, v[8:9]
	s_nop 0
	v_addc_co_u32_e32 v75, vcc, 0, v23, vcc
	v_add_co_u32_e32 v76, vcc, 0x4000, v22
	v_lshl_add_u64 v[70:71], v[22:23], 0, s[18:19]
	v_lshl_add_u64 v[72:73], v[22:23], 0, s[20:21]
	v_addc_co_u32_e32 v77, vcc, 0, v23, vcc
	global_load_dwordx4 v[22:25], v[74:75], off
	global_load_dwordx4 v[26:29], v[76:77], off
	global_load_dwordx4 v[30:33], v[12:13], off
	global_load_dwordx4 v[34:37], v[12:13], off offset:1024
	global_load_dwordx4 v[38:41], v[70:71], off offset:1024
	global_load_dwordx4 v[42:45], v[70:71], off offset:2048
	global_load_dwordx4 v[46:49], v[12:13], off offset:2048
	global_load_dwordx4 v[50:53], v[12:13], off offset:3072
	global_load_dwordx4 v[54:57], v[72:73], off offset:1024
	global_load_dwordx4 v[58:61], v[70:71], off offset:3072
	global_load_dwordx4 v[62:65], v[72:73], off offset:2048
	global_load_dwordx4 v[66:69], v[72:73], off offset:3072
	s_waitcnt vmcnt(0)
	v_pk_mul_f32 v[12:13], v[32:33], v[32:33]
	v_pk_mul_f32 v[70:71], v[30:31], v[30:31]
	v_mul_f32_e32 v2, v50, v50
	v_pk_mov_b32 v[72:73], v[70:71], v[12:13] op_sel:[1,0]
	v_mov_b32_e32 v71, v13
	v_pk_add_f32 v[12:13], v[72:73], v[70:71]
	v_pk_mul_f32 v[70:71], v[36:37], v[36:37]
	v_pk_mul_f32 v[72:73], v[34:35], v[34:35]
	v_pk_add_f32 v[12:13], v[12:13], v[12:13] op_sel:[0,1] op_sel_hi:[1,0]
	v_pk_mov_b32 v[74:75], v[72:73], v[70:71] op_sel:[1,0]
	v_mov_b32_e32 v73, v71
	v_pk_add_f32 v[70:71], v[74:75], v[72:73]
	v_mul_f32_e32 v72, v51, v51
	v_pk_add_f32 v[70:71], v[70:71], v[70:71] op_sel:[0,1] op_sel_hi:[1,0]
	v_mov_b32_e32 v13, v2
	v_mov_b32_e32 v71, v72
	v_mul_f32_e32 v2, v47, v47
	v_mul_f32_e32 v73, v52, v52
	v_pk_add_f32 v[12:13], v[12:13], v[70:71]
	v_pk_fma_f32 v[70:71], v[46:47], v[46:47], v[2:3] op_sel_hi:[1,1,0]
	v_mul_f32_e32 v2, v49, v49
	v_mul_f32_e32 v74, v53, v53
	v_mov_b32_e32 v71, v73
	v_pk_fma_f32 v[72:73], v[48:49], v[48:49], v[2:3] op_sel_hi:[1,1,0]
	v_pk_add_f32 v[26:27], v[26:27], 1.0 op_sel_hi:[1,0]
	v_mov_b32_e32 v73, v74
	v_pk_add_f32 v[70:71], v[70:71], v[72:73]
	v_lshlrev_b64 v[10:11], 11, v[10:11]
	v_pk_add_f32 v[12:13], v[12:13], v[70:71]
	v_lshl_add_u64 v[10:11], v[4:5], 0, v[10:11]
	v_add_f32_e32 v2, v12, v13
	s_nop 1
	v_add_f32_dpp v2, v2, v2 quad_perm:[1,0,3,2] row_mask:0xf bank_mask:0xf
	v_lshl_add_u64 v[0:1], v[0:1], 0, s[12:13]
	v_lshl_add_u64 v[6:7], v[6:7], 0, s[14:15]
	s_nop 1
	v_add_f32_dpp v2, v2, v2 quad_perm:[2,3,0,1] row_mask:0xf bank_mask:0xf
	s_nop 1
	v_add_f32_dpp v2, v2, v2 row_half_mirror row_mask:0xf bank_mask:0xf
	s_nop 1
	v_add_f32_dpp v2, v2, v2 row_mirror row_mask:0xf bank_mask:0xf
	s_nop 1
	v_add_f32_dpp v2, v2, v2 row_bcast:15 row_mask:0xa bank_mask:0xf
	s_nop 1
	v_add_f32_dpp v2, v2, v2 row_bcast:31 row_mask:0xc bank_mask:0xf
	s_nop 1
	v_readlane_b32 s98, v2, 63
	s_nop 3
	v_mov_b32_e32 v2, s98
	v_fmamk_f32 v2, v2, 0x3a800000, v21
	v_mul_f32_e32 v12, 0x4b800000, v2
	v_cmp_gt_f32_e32 vcc, s25, v2
	s_nop 1
	v_cndmask_b32_e32 v2, v2, v12, vcc
	v_rsq_f32_e32 v2, v2
	v_pk_add_f32 v[12:13], v[28:29], 1.0 op_sel_hi:[1,0]
	v_mul_f32_e32 v28, 0x45800000, v2
	v_cndmask_b32_e32 v2, v2, v28, vcc
	v_pk_mul_f32 v[28:29], v[30:31], v[2:3] op_sel_hi:[1,0]
	v_pk_mul_f32 v[30:31], v[32:33], v[2:3] op_sel_hi:[1,0]
	v_pk_fma_f32 v[22:23], v[26:27], v[28:29], v[22:23]
	v_pk_fma_f32 v[12:13], v[12:13], v[30:31], v[24:25]
	v_cvt_pk_bf16_f32 v22, v22, v23
	v_cvt_pk_bf16_f32 v23, v12, v13
	global_store_dwordx2 v[10:11], v[22:23], off
	v_pk_mul_f32 v[12:13], v[34:35], v[2:3] op_sel_hi:[1,0]
	v_pk_mul_f32 v[22:23], v[36:37], v[2:3] op_sel_hi:[1,0]
	v_pk_add_f32 v[24:25], v[56:57], 1.0 op_sel_hi:[1,0]
	v_pk_add_f32 v[26:27], v[54:55], 1.0 op_sel_hi:[1,0]
	v_pk_fma_f32 v[22:23], v[24:25], v[22:23], v[40:41]
	v_pk_fma_f32 v[12:13], v[26:27], v[12:13], v[38:39]
	v_pk_add_f32 v[24:25], v[64:65], 1.0 op_sel_hi:[1,0]
	v_cvt_pk_bf16_f32 v12, v12, v13
	v_cvt_pk_bf16_f32 v13, v22, v23
	global_store_dwordx2 v[10:11], v[12:13], off offset:512
	v_pk_mul_f32 v[12:13], v[46:47], v[2:3] op_sel_hi:[1,0]
	v_pk_mul_f32 v[22:23], v[48:49], v[2:3] op_sel_hi:[1,0]
	v_pk_add_f32 v[26:27], v[62:63], 1.0 op_sel_hi:[1,0]
	v_pk_fma_f32 v[22:23], v[24:25], v[22:23], v[44:45]
	v_pk_fma_f32 v[12:13], v[26:27], v[12:13], v[42:43]
	v_pk_add_f32 v[24:25], v[68:69], 1.0 op_sel_hi:[1,0]
	v_cvt_pk_bf16_f32 v12, v12, v13
	v_cvt_pk_bf16_f32 v13, v22, v23
	global_store_dwordx2 v[10:11], v[12:13], off offset:1024
	v_pk_mul_f32 v[12:13], v[50:51], v[2:3] op_sel_hi:[1,0]
	v_pk_mul_f32 v[22:23], v[52:53], v[2:3] op_sel_hi:[1,0]
	v_pk_add_f32 v[26:27], v[66:67], 1.0 op_sel_hi:[1,0]
	v_pk_fma_f32 v[22:23], v[24:25], v[22:23], v[60:61]
	v_pk_fma_f32 v[12:13], v[26:27], v[12:13], v[58:59]
	v_cmp_lt_i32_e32 vcc, s26, v0
	v_cvt_pk_bf16_f32 v12, v12, v13
	v_cvt_pk_bf16_f32 v13, v22, v23
	s_or_b64 s[16:17], vcc, s[16:17]
	global_store_dwordx2 v[10:11], v[12:13], off offset:1536
	s_andn2_b64 exec, exec, s[16:17]
	s_cbranch_execz .LBB0_422

.LBB0_1016:
	s_or_b64 exec, exec, s[22:23]
	v_cndmask_b32_e32 v2, 0, v20, vcc
	v_lshl_add_u64 v[22:23], s[10:11], 0, v[2:3]
	v_lshl_add_u64 v[22:23], v[22:23], 0, v[8:9]
	v_add_co_u32_e32 v74, vcc, 0x6000, v22
	v_lshl_add_u64 v[12:13], v[12:13], 0, v[8:9]
	s_nop 0
	v_addc_co_u32_e32 v75, vcc, 0, v23, vcc
	v_add_co_u32_e32 v76, vcc, 0x7000, v22
	v_lshl_add_u64 v[70:71], v[22:23], 0, s[18:19]
	v_lshl_add_u64 v[72:73], v[22:23], 0, s[20:21]
	v_addc_co_u32_e32 v77, vcc, 0, v23, vcc
	global_load_dwordx4 v[22:25], v[74:75], off
	global_load_dwordx4 v[26:29], v[76:77], off
	global_load_dwordx4 v[30:33], v[12:13], off
	global_load_dwordx4 v[34:37], v[12:13], off offset:1024
	global_load_dwordx4 v[38:41], v[70:71], off offset:1024
	global_load_dwordx4 v[42:45], v[70:71], off offset:2048
	global_load_dwordx4 v[46:49], v[12:13], off offset:2048
	global_load_dwordx4 v[50:53], v[12:13], off offset:3072
	global_load_dwordx4 v[54:57], v[72:73], off offset:1024
	global_load_dwordx4 v[58:61], v[70:71], off offset:3072
	global_load_dwordx4 v[62:65], v[72:73], off offset:2048
	global_load_dwordx4 v[66:69], v[72:73], off offset:3072
	s_waitcnt vmcnt(0)
	v_pk_mul_f32 v[12:13], v[32:33], v[32:33]
	v_pk_mul_f32 v[70:71], v[30:31], v[30:31]
	v_mul_f32_e32 v2, v50, v50
	v_pk_mov_b32 v[72:73], v[70:71], v[12:13] op_sel:[1,0]
	v_mov_b32_e32 v71, v13
	v_pk_add_f32 v[12:13], v[72:73], v[70:71]
	v_pk_mul_f32 v[70:71], v[36:37], v[36:37]
	v_pk_mul_f32 v[72:73], v[34:35], v[34:35]
	v_pk_add_f32 v[12:13], v[12:13], v[12:13] op_sel:[0,1] op_sel_hi:[1,0]
	v_pk_mov_b32 v[74:75], v[72:73], v[70:71] op_sel:[1,0]
	v_mov_b32_e32 v73, v71
	v_pk_add_f32 v[70:71], v[74:75], v[72:73]
	v_mul_f32_e32 v72, v51, v51
	v_pk_add_f32 v[70:71], v[70:71], v[70:71] op_sel:[0,1] op_sel_hi:[1,0]
	v_mov_b32_e32 v13, v2
	v_mov_b32_e32 v71, v72
	v_mul_f32_e32 v2, v47, v47
	v_mul_f32_e32 v73, v52, v52
	v_pk_add_f32 v[12:13], v[12:13], v[70:71]
	v_pk_fma_f32 v[70:71], v[46:47], v[46:47], v[2:3] op_sel_hi:[1,1,0]
	v_mul_f32_e32 v2, v49, v49
	v_mul_f32_e32 v74, v53, v53
	v_mov_b32_e32 v71, v73
	v_pk_fma_f32 v[72:73], v[48:49], v[48:49], v[2:3] op_sel_hi:[1,1,0]
	v_pk_add_f32 v[26:27], v[26:27], 1.0 op_sel_hi:[1,0]
	v_mov_b32_e32 v73, v74
	v_pk_add_f32 v[70:71], v[70:71], v[72:73]
	v_lshlrev_b64 v[10:11], 11, v[10:11]
	v_pk_add_f32 v[12:13], v[12:13], v[70:71]
	v_lshl_add_u64 v[10:11], v[4:5], 0, v[10:11]
	v_add_f32_e32 v2, v12, v13
	s_nop 1
	v_add_f32_dpp v2, v2, v2 quad_perm:[1,0,3,2] row_mask:0xf bank_mask:0xf
	v_lshl_add_u64 v[0:1], v[0:1], 0, s[12:13]
	v_lshl_add_u64 v[6:7], v[6:7], 0, s[14:15]
	s_nop 1
	v_add_f32_dpp v2, v2, v2 quad_perm:[2,3,0,1] row_mask:0xf bank_mask:0xf
	s_nop 1
	v_add_f32_dpp v2, v2, v2 row_half_mirror row_mask:0xf bank_mask:0xf
	s_nop 1
	v_add_f32_dpp v2, v2, v2 row_mirror row_mask:0xf bank_mask:0xf
	s_nop 1
	v_add_f32_dpp v2, v2, v2 row_bcast:15 row_mask:0xa bank_mask:0xf
	s_nop 1
	v_add_f32_dpp v2, v2, v2 row_bcast:31 row_mask:0xc bank_mask:0xf
	s_nop 1
	v_readlane_b32 s98, v2, 63
	s_nop 3
	v_mov_b32_e32 v2, s98
	v_fmamk_f32 v2, v2, 0x3a800000, v21
	v_mul_f32_e32 v12, 0x4b800000, v2
	v_cmp_gt_f32_e32 vcc, s25, v2
	s_nop 1
	v_cndmask_b32_e32 v2, v2, v12, vcc
	v_rsq_f32_e32 v2, v2
	v_pk_add_f32 v[12:13], v[28:29], 1.0 op_sel_hi:[1,0]
	v_mul_f32_e32 v28, 0x45800000, v2
	v_cndmask_b32_e32 v2, v2, v28, vcc
	v_pk_mul_f32 v[28:29], v[30:31], v[2:3] op_sel_hi:[1,0]
	v_pk_mul_f32 v[30:31], v[32:33], v[2:3] op_sel_hi:[1,0]
	v_pk_fma_f32 v[22:23], v[26:27], v[28:29], v[22:23]
	v_pk_fma_f32 v[12:13], v[12:13], v[30:31], v[24:25]
	v_cvt_pk_bf16_f32 v22, v22, v23
	v_cvt_pk_bf16_f32 v23, v12, v13
	global_store_dwordx2 v[10:11], v[22:23], off
	v_pk_mul_f32 v[12:13], v[34:35], v[2:3] op_sel_hi:[1,0]
	v_pk_mul_f32 v[22:23], v[36:37], v[2:3] op_sel_hi:[1,0]
	v_pk_add_f32 v[24:25], v[56:57], 1.0 op_sel_hi:[1,0]
	v_pk_add_f32 v[26:27], v[54:55], 1.0 op_sel_hi:[1,0]
	v_pk_fma_f32 v[22:23], v[24:25], v[22:23], v[40:41]
	v_pk_fma_f32 v[12:13], v[26:27], v[12:13], v[38:39]
	v_pk_add_f32 v[24:25], v[64:65], 1.0 op_sel_hi:[1,0]
	v_cvt_pk_bf16_f32 v12, v12, v13
	v_cvt_pk_bf16_f32 v13, v22, v23
	global_store_dwordx2 v[10:11], v[12:13], off offset:512
	v_pk_mul_f32 v[12:13], v[46:47], v[2:3] op_sel_hi:[1,0]
	v_pk_mul_f32 v[22:23], v[48:49], v[2:3] op_sel_hi:[1,0]
	v_pk_add_f32 v[26:27], v[62:63], 1.0 op_sel_hi:[1,0]
	v_pk_fma_f32 v[22:23], v[24:25], v[22:23], v[44:45]
	v_pk_fma_f32 v[12:13], v[26:27], v[12:13], v[42:43]
	v_pk_add_f32 v[24:25], v[68:69], 1.0 op_sel_hi:[1,0]
	v_cvt_pk_bf16_f32 v12, v12, v13
	v_cvt_pk_bf16_f32 v13, v22, v23
	global_store_dwordx2 v[10:11], v[12:13], off offset:1024
	v_pk_mul_f32 v[12:13], v[50:51], v[2:3] op_sel_hi:[1,0]
	v_pk_mul_f32 v[22:23], v[52:53], v[2:3] op_sel_hi:[1,0]
	v_pk_add_f32 v[26:27], v[66:67], 1.0 op_sel_hi:[1,0]
	v_pk_fma_f32 v[22:23], v[24:25], v[22:23], v[60:61]
	v_pk_fma_f32 v[12:13], v[26:27], v[12:13], v[58:59]
	v_cmp_lt_i32_e32 vcc, s26, v0
	v_cvt_pk_bf16_f32 v12, v12, v13
	v_cvt_pk_bf16_f32 v13, v22, v23
	s_or_b64 s[16:17], vcc, s[16:17]
	global_store_dwordx2 v[10:11], v[12:13], off offset:1536
	s_andn2_b64 exec, exec, s[16:17]
	s_cbranch_execz .LBB0_1019

.LBB0_1229:
	s_or_b64 exec, exec, s[20:21]
	v_cndmask_b32_e32 v2, 0, v20, vcc
	v_lshl_add_u64 v[22:23], s[10:11], 0, v[2:3]
	v_lshl_add_u64 v[70:71], v[22:23], 0, v[8:9]
	v_lshl_add_u64 v[12:13], v[12:13], 0, v[8:9]
	v_add_co_u32_e32 v74, vcc, 0x1000, v70
	v_lshl_add_u64 v[72:73], v[70:71], 0, s[18:19]
	s_nop 0
	v_addc_co_u32_e32 v75, vcc, 0, v71, vcc
	global_load_dwordx4 v[22:25], v[12:13], off
	global_load_dwordx4 v[26:29], v[12:13], off offset:1024
	global_load_dwordx4 v[30:33], v[70:71], off
	global_load_dwordx4 v[34:37], v[70:71], off offset:1024
	global_load_dwordx4 v[38:41], v[72:73], off offset:1024
	global_load_dwordx4 v[42:45], v[72:73], off offset:2048
	global_load_dwordx4 v[46:49], v[12:13], off offset:2048
	global_load_dwordx4 v[50:53], v[12:13], off offset:3072
	global_load_dwordx4 v[54:57], v[70:71], off offset:2048
	global_load_dwordx4 v[58:61], v[70:71], off offset:3072
	global_load_dwordx4 v[62:65], v[74:75], off
	global_load_dwordx4 v[66:69], v[72:73], off offset:3072
	s_waitcnt vmcnt(0)
	v_pk_mul_f32 v[12:13], v[24:25], v[24:25]
	v_pk_mul_f32 v[70:71], v[22:23], v[22:23]
	v_mul_f32_e32 v2, v50, v50
	v_pk_mov_b32 v[72:73], v[70:71], v[12:13] op_sel:[1,0]
	v_mov_b32_e32 v71, v13
	v_pk_add_f32 v[12:13], v[72:73], v[70:71]
	v_pk_mul_f32 v[70:71], v[28:29], v[28:29]
	v_pk_mul_f32 v[72:73], v[26:27], v[26:27]
	v_pk_add_f32 v[12:13], v[12:13], v[12:13] op_sel:[0,1] op_sel_hi:[1,0]
	v_pk_mov_b32 v[74:75], v[72:73], v[70:71] op_sel:[1,0]
	v_mov_b32_e32 v73, v71
	v_pk_add_f32 v[70:71], v[74:75], v[72:73]
	v_mul_f32_e32 v72, v51, v51
	v_pk_add_f32 v[70:71], v[70:71], v[70:71] op_sel:[0,1] op_sel_hi:[1,0]
	v_mov_b32_e32 v13, v2
	v_mov_b32_e32 v71, v72
	v_mul_f32_e32 v2, v47, v47
	v_mul_f32_e32 v73, v52, v52
	v_pk_add_f32 v[12:13], v[12:13], v[70:71]
	v_pk_fma_f32 v[70:71], v[46:47], v[46:47], v[2:3] op_sel_hi:[1,1,0]
	v_mul_f32_e32 v2, v49, v49
	v_mul_f32_e32 v74, v53, v53
	v_mov_b32_e32 v71, v73
	v_pk_fma_f32 v[72:73], v[48:49], v[48:49], v[2:3] op_sel_hi:[1,1,0]
	v_pk_add_f32 v[62:63], v[62:63], 1.0 op_sel_hi:[1,0]
	v_mov_b32_e32 v73, v74
	v_pk_add_f32 v[70:71], v[70:71], v[72:73]
	v_lshlrev_b64 v[10:11], 11, v[10:11]
	v_pk_add_f32 v[12:13], v[12:13], v[70:71]
	v_lshl_add_u64 v[10:11], v[4:5], 0, v[10:11]
	v_add_f32_e32 v2, v12, v13
	s_nop 1
	v_add_f32_dpp v2, v2, v2 quad_perm:[1,0,3,2] row_mask:0xf bank_mask:0xf
	v_lshl_add_u64 v[0:1], v[0:1], 0, s[12:13]
	v_lshl_add_u64 v[6:7], v[6:7], 0, s[14:15]
	s_nop 1
	v_add_f32_dpp v2, v2, v2 quad_perm:[2,3,0,1] row_mask:0xf bank_mask:0xf
	s_nop 1
	v_add_f32_dpp v2, v2, v2 row_half_mirror row_mask:0xf bank_mask:0xf
	s_nop 1
	v_add_f32_dpp v2, v2, v2 row_mirror row_mask:0xf bank_mask:0xf
	s_nop 1
	v_add_f32_dpp v2, v2, v2 row_bcast:15 row_mask:0xa bank_mask:0xf
	s_nop 1
	v_add_f32_dpp v2, v2, v2 row_bcast:31 row_mask:0xc bank_mask:0xf
	s_nop 1
	v_readlane_b32 s98, v2, 63
	s_nop 3
	v_mov_b32_e32 v2, s98
	v_fmamk_f32 v2, v2, 0x3a800000, v21
	v_mul_f32_e32 v12, 0x4b800000, v2
	v_cmp_gt_f32_e32 vcc, s23, v2
	s_nop 1
	v_cndmask_b32_e32 v2, v2, v12, vcc
	v_rsq_f32_e32 v2, v2
	v_pk_add_f32 v[12:13], v[64:65], 1.0 op_sel_hi:[1,0]
	v_mul_f32_e32 v64, 0x45800000, v2
	v_cndmask_b32_e32 v2, v2, v64, vcc
	v_pk_mul_f32 v[22:23], v[22:23], v[2:3] op_sel_hi:[1,0]
	v_pk_mul_f32 v[24:25], v[24:25], v[2:3] op_sel_hi:[1,0]
	v_pk_fma_f32 v[22:23], v[62:63], v[22:23], v[30:31]
	v_pk_fma_f32 v[12:13], v[12:13], v[24:25], v[32:33]
	v_cvt_pk_bf16_f32 v22, v22, v23
	v_cvt_pk_bf16_f32 v23, v12, v13
	global_store_dwordx2 v[10:11], v[22:23], off
	v_pk_mul_f32 v[12:13], v[26:27], v[2:3] op_sel_hi:[1,0]
	v_pk_mul_f32 v[22:23], v[28:29], v[2:3] op_sel_hi:[1,0]
	v_pk_add_f32 v[24:25], v[40:41], 1.0 op_sel_hi:[1,0]
	v_pk_add_f32 v[26:27], v[38:39], 1.0 op_sel_hi:[1,0]
	v_pk_fma_f32 v[22:23], v[24:25], v[22:23], v[36:37]
	v_pk_fma_f32 v[12:13], v[26:27], v[12:13], v[34:35]
	v_pk_add_f32 v[24:25], v[44:45], 1.0 op_sel_hi:[1,0]
	v_cvt_pk_bf16_f32 v12, v12, v13
	v_cvt_pk_bf16_f32 v13, v22, v23
	global_store_dwordx2 v[10:11], v[12:13], off offset:512
	v_pk_mul_f32 v[12:13], v[46:47], v[2:3] op_sel_hi:[1,0]
	v_pk_mul_f32 v[22:23], v[48:49], v[2:3] op_sel_hi:[1,0]
	v_pk_add_f32 v[26:27], v[42:43], 1.0 op_sel_hi:[1,0]
	v_pk_fma_f32 v[22:23], v[24:25], v[22:23], v[56:57]
	v_pk_fma_f32 v[12:13], v[26:27], v[12:13], v[54:55]
	v_pk_add_f32 v[24:25], v[68:69], 1.0 op_sel_hi:[1,0]
	v_cvt_pk_bf16_f32 v12, v12, v13
	v_cvt_pk_bf16_f32 v13, v22, v23
	global_store_dwordx2 v[10:11], v[12:13], off offset:1024
	v_pk_mul_f32 v[12:13], v[50:51], v[2:3] op_sel_hi:[1,0]
	v_pk_mul_f32 v[22:23], v[52:53], v[2:3] op_sel_hi:[1,0]
	v_pk_add_f32 v[26:27], v[66:67], 1.0 op_sel_hi:[1,0]
	v_pk_fma_f32 v[22:23], v[24:25], v[22:23], v[60:61]
	v_pk_fma_f32 v[12:13], v[26:27], v[12:13], v[58:59]
	v_cmp_lt_i32_e32 vcc, s24, v0
	v_cvt_pk_bf16_f32 v12, v12, v13
	v_cvt_pk_bf16_f32 v13, v22, v23
	s_or_b64 s[16:17], vcc, s[16:17]
	global_store_dwordx2 v[10:11], v[12:13], off offset:1536
	s_andn2_b64 exec, exec, s[16:17]
	s_cbranch_execz .LBB0_1232

.LBB0_2466:
	s_or_b64 exec, exec, s[22:23]
	v_cndmask_b32_e32 v2, 0, v22, vcc
	v_lshl_add_u64 v[24:25], s[10:11], 0, v[2:3]
	v_lshl_add_u64 v[24:25], v[24:25], 0, v[10:11]
	v_add_co_u32_e32 v76, vcc, 0x6000, v24
	v_lshl_add_u64 v[14:15], v[14:15], 0, v[10:11]
	s_nop 0
	v_addc_co_u32_e32 v77, vcc, 0, v25, vcc
	v_add_co_u32_e32 v78, vcc, 0x7000, v24
	v_lshl_add_u64 v[72:73], v[24:25], 0, s[18:19]
	v_lshl_add_u64 v[74:75], v[24:25], 0, s[20:21]
	v_addc_co_u32_e32 v79, vcc, 0, v25, vcc
	global_load_dwordx4 v[24:27], v[76:77], off
	global_load_dwordx4 v[28:31], v[78:79], off
	global_load_dwordx4 v[32:35], v[14:15], off
	global_load_dwordx4 v[36:39], v[14:15], off offset:1024
	global_load_dwordx4 v[40:43], v[72:73], off offset:1024
	global_load_dwordx4 v[44:47], v[72:73], off offset:2048
	global_load_dwordx4 v[48:51], v[14:15], off offset:2048
	global_load_dwordx4 v[52:55], v[14:15], off offset:3072
	global_load_dwordx4 v[56:59], v[74:75], off offset:1024
	global_load_dwordx4 v[60:63], v[72:73], off offset:3072
	global_load_dwordx4 v[64:67], v[74:75], off offset:2048
	global_load_dwordx4 v[68:71], v[74:75], off offset:3072
	s_waitcnt vmcnt(0)
	v_pk_mul_f32 v[14:15], v[34:35], v[34:35]
	v_pk_mul_f32 v[72:73], v[32:33], v[32:33]
	v_mul_f32_e32 v2, v52, v52
	v_pk_mov_b32 v[74:75], v[72:73], v[14:15] op_sel:[1,0]
	v_mov_b32_e32 v73, v15
	v_pk_add_f32 v[14:15], v[74:75], v[72:73]
	v_pk_mul_f32 v[72:73], v[38:39], v[38:39]
	v_pk_mul_f32 v[74:75], v[36:37], v[36:37]
	v_mul_f32_e32 v9, v53, v53
	v_pk_mov_b32 v[76:77], v[74:75], v[72:73] op_sel:[1,0]
	v_mov_b32_e32 v75, v73
	v_pk_add_f32 v[72:73], v[76:77], v[74:75]
	v_pk_add_f32 v[14:15], v[14:15], v[14:15] op_sel:[0,1] op_sel_hi:[1,0]
	v_pk_add_f32 v[72:73], v[72:73], v[72:73] op_sel:[0,1] op_sel_hi:[1,0]
	v_mov_b32_e32 v15, v2
	v_mov_b32_e32 v73, v9
	v_mul_f32_e32 v2, v49, v49
	v_mul_f32_e32 v74, v54, v54
	v_pk_add_f32 v[14:15], v[14:15], v[72:73]
	v_pk_fma_f32 v[72:73], v[48:49], v[48:49], v[2:3] op_sel_hi:[1,1,0]
	v_mul_f32_e32 v2, v51, v51
	v_mul_f32_e32 v76, v55, v55
	v_mov_b32_e32 v73, v74
	v_pk_fma_f32 v[74:75], v[50:51], v[50:51], v[2:3] op_sel_hi:[1,1,0]
	v_pk_add_f32 v[28:29], v[28:29], 1.0 op_sel_hi:[1,0]
	v_mov_b32_e32 v75, v76
	v_pk_add_f32 v[72:73], v[72:73], v[74:75]
	v_lshlrev_b64 v[12:13], 11, v[12:13]
	v_pk_add_f32 v[14:15], v[14:15], v[72:73]
	v_lshl_add_u64 v[12:13], v[4:5], 0, v[12:13]
	v_add_f32_e32 v2, v14, v15
	s_nop 1
	v_add_f32_dpp v2, v2, v2 quad_perm:[1,0,3,2] row_mask:0xf bank_mask:0xf
	v_pk_add_f32 v[14:15], v[30:31], 1.0 op_sel_hi:[1,0]
	v_add_u32_e32 v8, s12, v8
	v_lshl_add_u64 v[0:1], v[0:1], 0, s[12:13]
	v_lshl_add_u64 v[6:7], v[6:7], 0, s[14:15]
	s_nop 1
	v_add_f32_dpp v2, v2, v2 quad_perm:[2,3,0,1] row_mask:0xf bank_mask:0xf
	s_nop 1
	v_add_f32_dpp v2, v2, v2 row_half_mirror row_mask:0xf bank_mask:0xf
	s_nop 1
	v_add_f32_dpp v2, v2, v2 row_mirror row_mask:0xf bank_mask:0xf
	s_nop 1
	v_add_f32_dpp v2, v2, v2 row_bcast:15 row_mask:0xa bank_mask:0xf
	s_nop 1
	v_add_f32_dpp v2, v2, v2 row_bcast:31 row_mask:0xc bank_mask:0xf
	s_nop 1
	v_readlane_b32 s98, v2, 63
	s_nop 3
	v_mov_b32_e32 v2, s98
	v_fmamk_f32 v2, v2, 0x3a800000, v23
	v_mul_f32_e32 v9, 0x4b800000, v2
	v_cmp_gt_f32_e32 vcc, s25, v2
	s_nop 1
	v_cndmask_b32_e32 v2, v2, v9, vcc
	v_rsq_f32_e32 v2, v2
	s_nop 0
	v_mul_f32_e32 v9, 0x45800000, v2
	v_cndmask_b32_e32 v2, v2, v9, vcc
	v_pk_mul_f32 v[30:31], v[32:33], v[2:3] op_sel_hi:[1,0]
	v_pk_mul_f32 v[32:33], v[34:35], v[2:3] op_sel_hi:[1,0]
	v_pk_fma_f32 v[24:25], v[28:29], v[30:31], v[24:25]
	v_pk_fma_f32 v[14:15], v[14:15], v[32:33], v[26:27]
	v_cvt_pk_bf16_f32 v24, v24, v25
	v_cvt_pk_bf16_f32 v25, v14, v15
	global_store_dwordx2 v[12:13], v[24:25], off
	v_pk_mul_f32 v[14:15], v[36:37], v[2:3] op_sel_hi:[1,0]
	v_pk_mul_f32 v[24:25], v[38:39], v[2:3] op_sel_hi:[1,0]
	v_pk_add_f32 v[26:27], v[58:59], 1.0 op_sel_hi:[1,0]
	v_pk_add_f32 v[28:29], v[56:57], 1.0 op_sel_hi:[1,0]
	v_pk_fma_f32 v[24:25], v[26:27], v[24:25], v[42:43]
	v_pk_fma_f32 v[14:15], v[28:29], v[14:15], v[40:41]
	v_pk_add_f32 v[26:27], v[66:67], 1.0 op_sel_hi:[1,0]
	v_cvt_pk_bf16_f32 v14, v14, v15
	v_cvt_pk_bf16_f32 v15, v24, v25
	global_store_dwordx2 v[12:13], v[14:15], off offset:512
	v_pk_mul_f32 v[14:15], v[48:49], v[2:3] op_sel_hi:[1,0]
	v_pk_mul_f32 v[24:25], v[50:51], v[2:3] op_sel_hi:[1,0]
	v_pk_add_f32 v[28:29], v[64:65], 1.0 op_sel_hi:[1,0]
	v_pk_fma_f32 v[24:25], v[26:27], v[24:25], v[46:47]
	v_pk_fma_f32 v[14:15], v[28:29], v[14:15], v[44:45]
	v_pk_add_f32 v[26:27], v[70:71], 1.0 op_sel_hi:[1,0]
	v_cvt_pk_bf16_f32 v14, v14, v15
	v_cvt_pk_bf16_f32 v15, v24, v25
	global_store_dwordx2 v[12:13], v[14:15], off offset:1024
	v_pk_mul_f32 v[14:15], v[52:53], v[2:3] op_sel_hi:[1,0]
	v_pk_mul_f32 v[24:25], v[54:55], v[2:3] op_sel_hi:[1,0]
	v_pk_add_f32 v[28:29], v[68:69], 1.0 op_sel_hi:[1,0]
	v_add_u32_e32 v2, 0x100, v8
	v_pk_fma_f32 v[24:25], v[26:27], v[24:25], v[62:63]
	v_pk_fma_f32 v[14:15], v[28:29], v[14:15], v[60:61]
	v_cmp_lt_i32_e32 vcc, s26, v2
	v_cvt_pk_bf16_f32 v14, v14, v15
	v_cvt_pk_bf16_f32 v15, v24, v25
	s_or_b64 s[16:17], vcc, s[16:17]
	global_store_dwordx2 v[12:13], v[14:15], off offset:1536
	s_andn2_b64 exec, exec, s[16:17]
	s_cbranch_execz .LBB0_2469

.LBB0_2672:
	s_or_b64 exec, exec, s[20:21]
	v_cndmask_b32_e32 v2, 0, v22, vcc
	v_lshl_add_u64 v[24:25], s[10:11], 0, v[2:3]
	v_lshl_add_u64 v[72:73], v[24:25], 0, v[10:11]
	v_lshl_add_u64 v[14:15], v[14:15], 0, v[10:11]
	v_add_co_u32_e32 v76, vcc, 0x1000, v72
	v_lshl_add_u64 v[74:75], v[72:73], 0, s[18:19]
	s_nop 0
	v_addc_co_u32_e32 v77, vcc, 0, v73, vcc
	global_load_dwordx4 v[24:27], v[14:15], off
	global_load_dwordx4 v[28:31], v[14:15], off offset:1024
	global_load_dwordx4 v[32:35], v[72:73], off
	global_load_dwordx4 v[36:39], v[72:73], off offset:1024
	global_load_dwordx4 v[40:43], v[74:75], off offset:1024
	global_load_dwordx4 v[44:47], v[74:75], off offset:2048
	global_load_dwordx4 v[48:51], v[14:15], off offset:2048
	global_load_dwordx4 v[52:55], v[14:15], off offset:3072
	global_load_dwordx4 v[56:59], v[72:73], off offset:2048
	global_load_dwordx4 v[60:63], v[72:73], off offset:3072
	global_load_dwordx4 v[64:67], v[76:77], off
	global_load_dwordx4 v[68:71], v[74:75], off offset:3072
	s_waitcnt vmcnt(0)
	v_pk_mul_f32 v[14:15], v[26:27], v[26:27]
	v_pk_mul_f32 v[72:73], v[24:25], v[24:25]
	v_mul_f32_e32 v2, v52, v52
	v_pk_mov_b32 v[74:75], v[72:73], v[14:15] op_sel:[1,0]
	v_mov_b32_e32 v73, v15
	v_pk_add_f32 v[14:15], v[74:75], v[72:73]
	v_pk_mul_f32 v[72:73], v[30:31], v[30:31]
	v_pk_mul_f32 v[74:75], v[28:29], v[28:29]
	v_mul_f32_e32 v9, v53, v53
	v_pk_mov_b32 v[76:77], v[74:75], v[72:73] op_sel:[1,0]
	v_mov_b32_e32 v75, v73
	v_pk_add_f32 v[72:73], v[76:77], v[74:75]
	v_pk_add_f32 v[14:15], v[14:15], v[14:15] op_sel:[0,1] op_sel_hi:[1,0]
	v_pk_add_f32 v[72:73], v[72:73], v[72:73] op_sel:[0,1] op_sel_hi:[1,0]
	v_mov_b32_e32 v15, v2
	v_mov_b32_e32 v73, v9
	v_mul_f32_e32 v2, v49, v49
	v_mul_f32_e32 v74, v54, v54
	v_pk_add_f32 v[14:15], v[14:15], v[72:73]
	v_pk_fma_f32 v[72:73], v[48:49], v[48:49], v[2:3] op_sel_hi:[1,1,0]
	v_mul_f32_e32 v2, v51, v51
	v_mul_f32_e32 v76, v55, v55
	v_mov_b32_e32 v73, v74
	v_pk_fma_f32 v[74:75], v[50:51], v[50:51], v[2:3] op_sel_hi:[1,1,0]
	v_pk_add_f32 v[64:65], v[64:65], 1.0 op_sel_hi:[1,0]
	v_mov_b32_e32 v75, v76
	v_pk_add_f32 v[72:73], v[72:73], v[74:75]
	v_lshlrev_b64 v[12:13], 11, v[12:13]
	v_pk_add_f32 v[14:15], v[14:15], v[72:73]
	v_lshl_add_u64 v[12:13], v[4:5], 0, v[12:13]
	v_add_f32_e32 v2, v14, v15
	s_nop 1
	v_add_f32_dpp v2, v2, v2 quad_perm:[1,0,3,2] row_mask:0xf bank_mask:0xf
	v_pk_add_f32 v[14:15], v[66:67], 1.0 op_sel_hi:[1,0]
	v_add_u32_e32 v8, s12, v8
	v_lshl_add_u64 v[0:1], v[0:1], 0, s[12:13]
	v_lshl_add_u64 v[6:7], v[6:7], 0, s[14:15]
	s_nop 1
	v_add_f32_dpp v2, v2, v2 quad_perm:[2,3,0,1] row_mask:0xf bank_mask:0xf
	s_nop 1
	v_add_f32_dpp v2, v2, v2 row_half_mirror row_mask:0xf bank_mask:0xf
	s_nop 1
	v_add_f32_dpp v2, v2, v2 row_mirror row_mask:0xf bank_mask:0xf
	s_nop 1
	v_add_f32_dpp v2, v2, v2 row_bcast:15 row_mask:0xa bank_mask:0xf
	s_nop 1
	v_add_f32_dpp v2, v2, v2 row_bcast:31 row_mask:0xc bank_mask:0xf
	s_nop 1
	v_readlane_b32 s98, v2, 63
	s_nop 3
	v_mov_b32_e32 v2, s98
	v_fmamk_f32 v2, v2, 0x3a800000, v23
	v_mul_f32_e32 v9, 0x4b800000, v2
	v_cmp_gt_f32_e32 vcc, s23, v2
	s_nop 1
	v_cndmask_b32_e32 v2, v2, v9, vcc
	v_rsq_f32_e32 v2, v2
	s_nop 0
	v_mul_f32_e32 v9, 0x45800000, v2
	v_cndmask_b32_e32 v2, v2, v9, vcc
	v_pk_mul_f32 v[24:25], v[24:25], v[2:3] op_sel_hi:[1,0]
	v_pk_mul_f32 v[26:27], v[26:27], v[2:3] op_sel_hi:[1,0]
	v_pk_fma_f32 v[24:25], v[64:65], v[24:25], v[32:33]
	v_pk_fma_f32 v[14:15], v[14:15], v[26:27], v[34:35]
	v_cvt_pk_bf16_f32 v24, v24, v25
	v_cvt_pk_bf16_f32 v25, v14, v15
	global_store_dwordx2 v[12:13], v[24:25], off
	v_pk_mul_f32 v[14:15], v[28:29], v[2:3] op_sel_hi:[1,0]
	v_pk_mul_f32 v[24:25], v[30:31], v[2:3] op_sel_hi:[1,0]
	v_pk_add_f32 v[26:27], v[42:43], 1.0 op_sel_hi:[1,0]
	v_pk_add_f32 v[28:29], v[40:41], 1.0 op_sel_hi:[1,0]
	v_pk_fma_f32 v[24:25], v[26:27], v[24:25], v[38:39]
	v_pk_fma_f32 v[14:15], v[28:29], v[14:15], v[36:37]
	v_pk_add_f32 v[26:27], v[46:47], 1.0 op_sel_hi:[1,0]
	v_cvt_pk_bf16_f32 v14, v14, v15
	v_cvt_pk_bf16_f32 v15, v24, v25
	global_store_dwordx2 v[12:13], v[14:15], off offset:512
	v_pk_mul_f32 v[14:15], v[48:49], v[2:3] op_sel_hi:[1,0]
	v_pk_mul_f32 v[24:25], v[50:51], v[2:3] op_sel_hi:[1,0]
	v_pk_add_f32 v[28:29], v[44:45], 1.0 op_sel_hi:[1,0]
	v_pk_fma_f32 v[24:25], v[26:27], v[24:25], v[58:59]
	v_pk_fma_f32 v[14:15], v[28:29], v[14:15], v[56:57]
	v_pk_add_f32 v[26:27], v[70:71], 1.0 op_sel_hi:[1,0]
	v_cvt_pk_bf16_f32 v14, v14, v15
	v_cvt_pk_bf16_f32 v15, v24, v25
	global_store_dwordx2 v[12:13], v[14:15], off offset:1024
	v_pk_mul_f32 v[14:15], v[52:53], v[2:3] op_sel_hi:[1,0]
	v_pk_mul_f32 v[24:25], v[54:55], v[2:3] op_sel_hi:[1,0]
	v_pk_add_f32 v[28:29], v[68:69], 1.0 op_sel_hi:[1,0]
	v_add_u32_e32 v2, 0x100, v8
	v_pk_fma_f32 v[24:25], v[26:27], v[24:25], v[62:63]
	v_pk_fma_f32 v[14:15], v[28:29], v[14:15], v[60:61]
	v_cmp_lt_i32_e32 vcc, s24, v2
	v_cvt_pk_bf16_f32 v14, v14, v15
	v_cvt_pk_bf16_f32 v15, v24, v25
	s_or_b64 s[16:17], vcc, s[16:17]
	global_store_dwordx2 v[12:13], v[14:15], off offset:1536
	s_andn2_b64 exec, exec, s[16:17]
	s_cbranch_execz .LBB0_2675

.LBB0_2878:
	s_or_b64 exec, exec, s[22:23]
	v_cndmask_b32_e32 v2, 0, v22, vcc
	v_lshl_add_u64 v[24:25], s[10:11], 0, v[2:3]
	v_lshl_add_u64 v[24:25], v[24:25], 0, v[10:11]
	v_add_co_u32_e32 v76, vcc, 0x3000, v24
	v_lshl_add_u64 v[14:15], v[14:15], 0, v[10:11]
	s_nop 0
	v_addc_co_u32_e32 v77, vcc, 0, v25, vcc
	v_add_co_u32_e32 v78, vcc, 0x4000, v24
	v_lshl_add_u64 v[72:73], v[24:25], 0, s[18:19]
	v_lshl_add_u64 v[74:75], v[24:25], 0, s[20:21]
	v_addc_co_u32_e32 v79, vcc, 0, v25, vcc
	global_load_dwordx4 v[24:27], v[76:77], off
	global_load_dwordx4 v[28:31], v[78:79], off
	global_load_dwordx4 v[32:35], v[14:15], off
	global_load_dwordx4 v[36:39], v[14:15], off offset:1024
	global_load_dwordx4 v[40:43], v[72:73], off offset:1024
	global_load_dwordx4 v[44:47], v[72:73], off offset:2048
	global_load_dwordx4 v[48:51], v[14:15], off offset:2048
	global_load_dwordx4 v[52:55], v[14:15], off offset:3072
	global_load_dwordx4 v[56:59], v[74:75], off offset:1024
	global_load_dwordx4 v[60:63], v[72:73], off offset:3072
	global_load_dwordx4 v[64:67], v[74:75], off offset:2048
	global_load_dwordx4 v[68:71], v[74:75], off offset:3072
	s_waitcnt vmcnt(0)
	v_pk_mul_f32 v[14:15], v[34:35], v[34:35]
	v_pk_mul_f32 v[72:73], v[32:33], v[32:33]
	v_mul_f32_e32 v2, v52, v52
	v_pk_mov_b32 v[74:75], v[72:73], v[14:15] op_sel:[1,0]
	v_mov_b32_e32 v73, v15
	v_pk_add_f32 v[14:15], v[74:75], v[72:73]
	v_pk_mul_f32 v[72:73], v[38:39], v[38:39]
	v_pk_mul_f32 v[74:75], v[36:37], v[36:37]
	v_mul_f32_e32 v9, v53, v53
	v_pk_mov_b32 v[76:77], v[74:75], v[72:73] op_sel:[1,0]
	v_mov_b32_e32 v75, v73
	v_pk_add_f32 v[72:73], v[76:77], v[74:75]
	v_pk_add_f32 v[14:15], v[14:15], v[14:15] op_sel:[0,1] op_sel_hi:[1,0]
	v_pk_add_f32 v[72:73], v[72:73], v[72:73] op_sel:[0,1] op_sel_hi:[1,0]
	v_mov_b32_e32 v15, v2
	v_mov_b32_e32 v73, v9
	v_mul_f32_e32 v2, v49, v49
	v_mul_f32_e32 v74, v54, v54
	v_pk_add_f32 v[14:15], v[14:15], v[72:73]
	v_pk_fma_f32 v[72:73], v[48:49], v[48:49], v[2:3] op_sel_hi:[1,1,0]
	v_mul_f32_e32 v2, v51, v51
	v_mul_f32_e32 v76, v55, v55
	v_mov_b32_e32 v73, v74
	v_pk_fma_f32 v[74:75], v[50:51], v[50:51], v[2:3] op_sel_hi:[1,1,0]
	v_pk_add_f32 v[28:29], v[28:29], 1.0 op_sel_hi:[1,0]
	v_mov_b32_e32 v75, v76
	v_pk_add_f32 v[72:73], v[72:73], v[74:75]
	v_lshlrev_b64 v[12:13], 11, v[12:13]
	v_pk_add_f32 v[14:15], v[14:15], v[72:73]
	v_lshl_add_u64 v[12:13], v[4:5], 0, v[12:13]
	v_add_f32_e32 v2, v14, v15
	s_nop 1
	v_add_f32_dpp v2, v2, v2 quad_perm:[1,0,3,2] row_mask:0xf bank_mask:0xf
	v_pk_add_f32 v[14:15], v[30:31], 1.0 op_sel_hi:[1,0]
	v_add_u32_e32 v8, s12, v8
	v_lshl_add_u64 v[0:1], v[0:1], 0, s[12:13]
	v_lshl_add_u64 v[6:7], v[6:7], 0, s[14:15]
	s_nop 1
	v_add_f32_dpp v2, v2, v2 quad_perm:[2,3,0,1] row_mask:0xf bank_mask:0xf
	s_nop 1
	v_add_f32_dpp v2, v2, v2 row_half_mirror row_mask:0xf bank_mask:0xf
	s_nop 1
	v_add_f32_dpp v2, v2, v2 row_mirror row_mask:0xf bank_mask:0xf
	s_nop 1
	v_add_f32_dpp v2, v2, v2 row_bcast:15 row_mask:0xa bank_mask:0xf
	s_nop 1
	v_add_f32_dpp v2, v2, v2 row_bcast:31 row_mask:0xc bank_mask:0xf
	s_nop 1
	v_readlane_b32 s98, v2, 63
	s_nop 3
	v_mov_b32_e32 v2, s98
	v_fmamk_f32 v2, v2, 0x3a800000, v23
	v_mul_f32_e32 v9, 0x4b800000, v2
	v_cmp_gt_f32_e32 vcc, s25, v2
	s_nop 1
	v_cndmask_b32_e32 v2, v2, v9, vcc
	v_rsq_f32_e32 v2, v2
	s_nop 0
	v_mul_f32_e32 v9, 0x45800000, v2
	v_cndmask_b32_e32 v2, v2, v9, vcc
	v_pk_mul_f32 v[30:31], v[32:33], v[2:3] op_sel_hi:[1,0]
	v_pk_mul_f32 v[32:33], v[34:35], v[2:3] op_sel_hi:[1,0]
	v_pk_fma_f32 v[24:25], v[28:29], v[30:31], v[24:25]
	v_pk_fma_f32 v[14:15], v[14:15], v[32:33], v[26:27]
	v_cvt_pk_bf16_f32 v24, v24, v25
	v_cvt_pk_bf16_f32 v25, v14, v15
	global_store_dwordx2 v[12:13], v[24:25], off
	v_pk_mul_f32 v[14:15], v[36:37], v[2:3] op_sel_hi:[1,0]
	v_pk_mul_f32 v[24:25], v[38:39], v[2:3] op_sel_hi:[1,0]
	v_pk_add_f32 v[26:27], v[58:59], 1.0 op_sel_hi:[1,0]
	v_pk_add_f32 v[28:29], v[56:57], 1.0 op_sel_hi:[1,0]
	v_pk_fma_f32 v[24:25], v[26:27], v[24:25], v[42:43]
	v_pk_fma_f32 v[14:15], v[28:29], v[14:15], v[40:41]
	v_pk_add_f32 v[26:27], v[66:67], 1.0 op_sel_hi:[1,0]
	v_cvt_pk_bf16_f32 v14, v14, v15
	v_cvt_pk_bf16_f32 v15, v24, v25
	global_store_dwordx2 v[12:13], v[14:15], off offset:512
	v_pk_mul_f32 v[14:15], v[48:49], v[2:3] op_sel_hi:[1,0]
	v_pk_mul_f32 v[24:25], v[50:51], v[2:3] op_sel_hi:[1,0]
	v_pk_add_f32 v[28:29], v[64:65], 1.0 op_sel_hi:[1,0]
	v_pk_fma_f32 v[24:25], v[26:27], v[24:25], v[46:47]
	v_pk_fma_f32 v[14:15], v[28:29], v[14:15], v[44:45]
	v_pk_add_f32 v[26:27], v[70:71], 1.0 op_sel_hi:[1,0]
	v_cvt_pk_bf16_f32 v14, v14, v15
	v_cvt_pk_bf16_f32 v15, v24, v25
	global_store_dwordx2 v[12:13], v[14:15], off offset:1024
	v_pk_mul_f32 v[14:15], v[52:53], v[2:3] op_sel_hi:[1,0]
	v_pk_mul_f32 v[24:25], v[54:55], v[2:3] op_sel_hi:[1,0]
	v_pk_add_f32 v[28:29], v[68:69], 1.0 op_sel_hi:[1,0]
	v_add_u32_e32 v2, 0x100, v8
	v_pk_fma_f32 v[24:25], v[26:27], v[24:25], v[62:63]
	v_pk_fma_f32 v[14:15], v[28:29], v[14:15], v[60:61]
	v_cmp_lt_i32_e32 vcc, s26, v2
	v_cvt_pk_bf16_f32 v14, v14, v15
	v_cvt_pk_bf16_f32 v15, v24, v25
	s_or_b64 s[16:17], vcc, s[16:17]
	global_store_dwordx2 v[12:13], v[14:15], off offset:1536
	s_andn2_b64 exec, exec, s[16:17]
	s_cbranch_execz .LBB0_2881
